# v52 + attention: the last unit of a workgroup no longer re-fetches itself as a dummy next unit (16 loads / 128 KB per workgroup per pass dropped; skip path drains vmcnt)
# speedup vs baseline: 1.0059x; 1.0031x over previous
; __device__ __forceinline__ void attn_phase(LAS unsigned char* lds, const bf16* Qg, const bf16* Kg, const bf16* Vg  , bf16* OB, float* LSE, int g, int dsh, int u_lo, int u_hi) {
;     ...
;         { const int un0 = u + (int)gridDim.x; const int un = un0 < u_hi ? un0 : u;
;             ATTN_DECODE(un, hn, Q0n, tbn) ATTN_FETCH(hn, Q0n, tbn); }
.Lmy_attn_skippre:
	s_waitcnt vmcnt(0)
	s_branch .Lmy_attn_postpre

; __device__ __forceinline__ void attn_phase(LAS unsigned char* lds, const bf16* Qg, const bf16* Kg, const bf16* Vg  , bf16* OB, float* LSE, int g, int dsh, int u_lo, int u_hi) {
;     ...
;         { const int un0 = u + (int)gridDim.x; const int un = un0 < u_hi ? un0 : u;
;             ATTN_DECODE(un, hn, Q0n, tbn) ATTN_FETCH(hn, Q0n, tbn); }
.Lmy_attn_nopre:
	s_and_b32 s101, s36, 0xfff
	s_lshl_b32 s101, s101, 12
	s_lshr_b32 s101, s101, s30
	s_andn2_b32 s100, s36, 0xfff
	s_lshl_b32 s100, s100, 4
	s_add_i32 s100, s100, s101
	s_and_b32 s101, s94, 15
	s_lshl_b32 s101, s101, 12
	s_add_i32 s100, s100, s101
	s_mov_b32 s101, 0
	v_max_i32_e32 v4, 0, v3
	v_mov_b32_e32 v5, v1
	v_lshlrev_b64 v[4:5], 0, v[4:5]
	v_mov_b32_e32 v19, s8
	v_mov_b32_e32 v20, s11
	v_mov_b32_e32 v21, s9
	v_mov_b32_e32 v22, s10
	v_lshl_add_u64 v[4:5], v[4:5], 0, s[100:101]
	v_cndmask_b32_e64 v7, v19, v20, s[40:41]
	v_cndmask_b32_e64 v6, v21, v22, s[40:41]
	v_lshlrev_b64 v[4:5], 7, v[4:5]
	s_lshl_b32 s40, s94, 7
	v_lshl_add_u64 v[4:5], v[6:7], 0, v[4:5]
	s_and_b32 s94, s40, 0x780
	v_lshl_add_u64 v[4:5], v[4:5], 0, 0
	v_mov_b32_e32 v3, v1
	s_waitcnt lgkmcnt(0)
	s_barrier
	s_cmp_lg_u64 s[20:21], 0
	s_cbranch_scc1 .Lmy_attn_skippre
	v_add_u32_e32 v252, s23, v169
	v_add_u32_e32 v252, s14, v252
	v_add_u32_e32 v252, 0x80, v252
	v_mov_b32_e32 v253, 0
	v_lshl_add_u64 v[252:253], v[252:253], 0, s[100:101]
	v_lshlrev_b64 v[252:253], 7, v[252:253]
	v_lshl_add_u64 v[252:253], s[68:69], 0, v[252:253]
	v_lshl_add_u64 v[252:253], v[252:253], 0, v[0:1]
	global_load_dwordx4 v[232:235], v[252:253], off
	global_load_dwordx4 v[236:239], v[252:253], off offset:32
	global_load_dwordx4 v[240:243], v[252:253], off offset:64
	global_load_dwordx4 v[244:247], v[252:253], off offset:96
	v_lshl_add_u64 v[4:5], v[4:5], 0, v[2:3]
	global_load_dwordx4 v[82:85], v[4:5], off
	v_add_u32_e32 v4, s23, v8
	v_max_i32_e32 v4, 0, v4
	v_mov_b32_e32 v5, v1
	v_lshlrev_b64 v[4:5], 0, v[4:5]
	v_lshl_add_u64 v[4:5], v[4:5], 0, s[100:101]
	v_cndmask_b32_e32 v7, v19, v20, vcc
	v_cndmask_b32_e32 v6, v21, v22, vcc
	v_lshlrev_b64 v[4:5], 7, v[4:5]
	v_lshl_add_u64 v[4:5], v[6:7], 0, v[4:5]
	v_lshl_add_u64 v[4:5], v[4:5], 0, 0
	v_lshl_add_u64 v[4:5], v[4:5], 0, v[2:3]
	global_load_dwordx4 v[86:89], v[4:5], off
	v_add_u32_e32 v4, s23, v9
	v_max_i32_e32 v4, 0, v4
	v_mov_b32_e32 v5, v1
	v_lshlrev_b64 v[4:5], 0, v[4:5]
	v_lshl_add_u64 v[4:5], v[4:5], 0, s[100:101]
	v_cndmask_b32_e64 v7, v19, v20, s[38:39]
	v_cndmask_b32_e64 v6, v21, v22, s[38:39]
	v_lshlrev_b64 v[4:5], 7, v[4:5]
	v_lshl_add_u64 v[4:5], v[6:7], 0, v[4:5]
	v_lshl_add_u64 v[4:5], v[4:5], 0, 0
	v_lshl_add_u64 v[4:5], v[4:5], 0, v[2:3]
	global_load_dwordx4 v[90:93], v[4:5], off
	v_add_u32_e32 v4, s23, v10
	v_max_i32_e32 v4, 0, v4
	v_mov_b32_e32 v5, v1
	v_lshlrev_b64 v[4:5], 0, v[4:5]
	v_lshl_add_u64 v[4:5], v[4:5], 0, s[100:101]
	v_cndmask_b32_e64 v7, v19, v20, s[42:43]
	v_cndmask_b32_e64 v6, v21, v22, s[42:43]
	v_lshlrev_b64 v[4:5], 7, v[4:5]
	v_lshl_add_u64 v[4:5], v[6:7], 0, v[4:5]
	v_lshl_add_u64 v[4:5], v[4:5], 0, 0
	v_lshl_add_u64 v[4:5], v[4:5], 0, v[2:3]
	global_load_dwordx4 v[94:97], v[4:5], off
	v_add_u32_e32 v4, s23, v11
	v_max_i32_e32 v4, 0, v4
	v_mov_b32_e32 v5, v1
	v_lshlrev_b64 v[4:5], 0, v[4:5]
	v_lshl_add_u64 v[4:5], v[4:5], 0, s[100:101]
	v_cndmask_b32_e64 v7, v19, v20, s[44:45]
	v_cndmask_b32_e64 v6, v21, v22, s[44:45]
	v_lshlrev_b64 v[4:5], 7, v[4:5]
	v_lshl_add_u64 v[4:5], v[6:7], 0, v[4:5]
	v_lshl_add_u64 v[4:5], v[4:5], 0, 0
	v_lshl_add_u64 v[4:5], v[4:5], 0, v[2:3]
	global_load_dwordx4 v[98:101], v[4:5], off
	v_add_u32_e32 v4, s23, v12
	v_max_i32_e32 v4, 0, v4
	v_mov_b32_e32 v5, v1
	v_lshlrev_b64 v[4:5], 0, v[4:5]
	v_lshl_add_u64 v[4:5], v[4:5], 0, s[100:101]
	v_cndmask_b32_e64 v7, v19, v20, s[46:47]
	v_cndmask_b32_e64 v6, v21, v22, s[46:47]
	v_lshlrev_b64 v[4:5], 7, v[4:5]
	v_lshl_add_u64 v[4:5], v[6:7], 0, v[4:5]
	v_lshl_add_u64 v[4:5], v[4:5], 0, 0
	v_lshl_add_u64 v[4:5], v[4:5], 0, v[2:3]
	global_load_dwordx4 v[102:105], v[4:5], off
	v_add_u32_e32 v4, s23, v13
	v_max_i32_e32 v4, 0, v4
	v_mov_b32_e32 v5, v1
	v_lshlrev_b64 v[4:5], 0, v[4:5]
	v_lshl_add_u64 v[4:5], v[4:5], 0, s[100:101]
	v_cndmask_b32_e64 v7, v19, v20, s[48:49]
	v_cndmask_b32_e64 v6, v21, v22, s[48:49]
	v_lshlrev_b64 v[4:5], 7, v[4:5]
	v_lshl_add_u64 v[4:5], v[6:7], 0, v[4:5]
	v_lshl_add_u64 v[4:5], v[4:5], 0, 0
	v_lshl_add_u64 v[4:5], v[4:5], 0, v[2:3]
	global_load_dwordx4 v[106:109], v[4:5], off
	v_add_u32_e32 v4, s23, v14
	v_max_i32_e32 v4, 0, v4
	v_mov_b32_e32 v5, v1
	v_lshlrev_b64 v[4:5], 0, v[4:5]
	v_lshl_add_u64 v[4:5], v[4:5], 0, s[100:101]
	v_cndmask_b32_e64 v7, v19, v20, s[50:51]
	v_cndmask_b32_e64 v6, v21, v22, s[50:51]
	v_lshlrev_b64 v[4:5], 7, v[4:5]
	v_lshl_add_u64 v[4:5], v[6:7], 0, v[4:5]
	v_lshl_add_u64 v[4:5], v[4:5], 0, 0
	v_lshl_add_u64 v[4:5], v[4:5], 0, v[2:3]
	global_load_dwordx4 v[110:113], v[4:5], off
	v_add_u32_e32 v4, s23, v15
	v_max_i32_e32 v4, 0, v4
	v_mov_b32_e32 v5, v1
	v_lshlrev_b64 v[4:5], 0, v[4:5]
	v_lshl_add_u64 v[4:5], v[4:5], 0, s[100:101]
	v_cndmask_b32_e64 v7, v19, v20, s[52:53]
	v_cndmask_b32_e64 v6, v21, v22, s[52:53]
	v_lshlrev_b64 v[4:5], 7, v[4:5]
	v_lshl_add_u64 v[4:5], v[6:7], 0, v[4:5]
	v_lshl_add_u64 v[4:5], v[4:5], 0, 0
	v_lshl_add_u64 v[4:5], v[4:5], 0, v[2:3]
	global_load_dwordx4 v[114:117], v[4:5], off
	v_add_u32_e32 v4, s23, v16
	v_max_i32_e32 v4, 0, v4
	v_mov_b32_e32 v5, v1
	v_lshlrev_b64 v[4:5], 0, v[4:5]
	v_lshl_add_u64 v[4:5], v[4:5], 0, s[100:101]
	v_cndmask_b32_e64 v7, v19, v20, s[54:55]
	v_cndmask_b32_e64 v6, v21, v22, s[54:55]
	v_lshlrev_b64 v[4:5], 7, v[4:5]
	v_lshl_add_u64 v[4:5], v[6:7], 0, v[4:5]
	v_lshl_add_u64 v[4:5], v[4:5], 0, 0
	v_lshl_add_u64 v[4:5], v[4:5], 0, v[2:3]
	global_load_dwordx4 v[118:121], v[4:5], off
	v_add_u32_e32 v4, s23, v17
	v_max_i32_e32 v4, 0, v4
	v_mov_b32_e32 v5, v1
	v_lshlrev_b64 v[4:5], 0, v[4:5]
	v_lshl_add_u64 v[4:5], v[4:5], 0, s[100:101]
	v_cndmask_b32_e64 v7, v19, v20, s[56:57]
	v_cndmask_b32_e64 v6, v21, v22, s[56:57]
	v_lshlrev_b64 v[4:5], 7, v[4:5]
	v_lshl_add_u64 v[4:5], v[6:7], 0, v[4:5]
	v_lshl_add_u64 v[4:5], v[4:5], 0, 0
	v_lshl_add_u64 v[4:5], v[4:5], 0, v[2:3]
	global_load_dwordx4 v[122:125], v[4:5], off
	v_add_u32_e32 v4, s23, v18
	v_max_i32_e32 v4, 0, v4
	v_mov_b32_e32 v5, v1
	v_lshlrev_b64 v[4:5], 0, v[4:5]
	v_lshl_add_u64 v[4:5], v[4:5], 0, s[100:101]
	v_cndmask_b32_e64 v7, v19, v20, s[58:59]
	v_cndmask_b32_e64 v6, v21, v22, s[58:59]
	v_lshlrev_b64 v[4:5], 7, v[4:5]
	v_lshl_add_u64 v[4:5], v[6:7], 0, v[4:5]
	v_lshl_add_u64 v[4:5], v[4:5], 0, 0
	v_lshl_add_u64 v[2:3], v[4:5], 0, v[2:3]
	global_load_dwordx4 v[126:129], v[2:3], off
; #define LAS __attribute__((address_space(3)))
; #define MFMA32(a, b, c) __builtin_amdgcn_mfma_f32_32x32x16_bf16((a), (b), (c), 0, 0, 0)
; __device__ __forceinline__ void attn_phase(LAS unsigned char* lds, const bf16* Qg, const bf16* Kg, const bf16* Vg  , bf16* OB, float* LSE, int g, int dsh, int u_lo, int u_hi) {
;     ...
;         f32x16 st[5];
;         const bool first = (Q0 == 0);
; #pragma unroll
;         for (int c = 0; c < 5; ++c) {
; #pragma unroll
;             for (int i = 0; i < 16; ++i) st[c][i] = 0.f;
;             if (!(first && (wave + c < 4)))
; #pragma unroll
;             for (int ks = 0; ks < 4; ++ks) { const bf16x8 kf = *(const LAS bf16x8*)(Kl + (32 * (wave + c) + r) * AT_PITCH + (16 * ks + 8 * hh) * 2); st[c] = MFMA32(kf, qf[ks], st[c]); } }
.Lmy_attn_postpre:
	s_cmp_lg_u32 s79, 0
	s_cselect_b64 s[38:39], -1, 0
	s_or_b64 s[54:55], s[38:39], s[90:91]
	v_cndmask_b32_e64 v3, 0, 1, s[54:55]
	v_add_u32_e32 v0, 0, v0
	v_mov_b32_e32 v2, 0
	v_cmp_ne_u32_e64 s[46:47], 1, v3
	s_andn2_b64 vcc, exec, s[54:55]
	v_mov_b32_e32 v18, 0
	v_mov_b32_e32 v19, 0
	v_mov_b32_e32 v20, 0
	v_mov_b32_e32 v21, 0
	v_mov_b32_e32 v22, 0
	v_mov_b32_e32 v23, 0
	v_mov_b32_e32 v24, 0
	v_mov_b32_e32 v25, 0
	v_mov_b32_e32 v26, 0
	v_mov_b32_e32 v27, 0
	v_mov_b32_e32 v28, 0
	v_mov_b32_e32 v29, 0
	v_mov_b32_e32 v30, 0
	v_mov_b32_e32 v31, 0
	v_mov_b32_e32 v32, 0
	v_mov_b32_e32 v33, 0
	s_cbranch_vccnz .LBB0_143
	v_or_b32_e32 v3, s14, v169
	v_mad_u64_u32 v[8:9], s[36:37], v3, s97, v[0:1]
	ds_read_b128 v[4:7], v8
	s_waitcnt lgkmcnt(0)
	v_mfma_f32_32x32x16_bf16 v[18:33], v[4:7], v[158:161], 0
	ds_read_b128 v[4:7], v8 offset:32
	s_waitcnt lgkmcnt(0)
	v_mfma_f32_32x32x16_bf16 v[18:33], v[4:7], v[154:157], v[18:33]
	ds_read_b128 v[4:7], v8 offset:64
	s_waitcnt lgkmcnt(0)
	v_mfma_f32_32x32x16_bf16 v[18:33], v[4:7], v[150:153], v[18:33]
	ds_read_b128 v[4:7], v8 offset:96
	s_waitcnt lgkmcnt(0)
	v_mfma_f32_32x32x16_bf16 v[18:33], v[4:7], v[146:149], v[18:33]
